# v9: v4 + dilated window mask by one unsigned range compare per element and exps without redundant mask re-apply; sb loop NaN-canonicalise v_max folded
# speedup vs baseline: 1.0060x; 1.0046x over previous
.LBB0_376:
	s_cmpk_gt_i32 s78, 0x5ff
	s_mov_b64 s[0:1], -1
	s_cbranch_scc0 .LBB0_398
	s_add_i32 s0, s78, 0xfffffa00
	s_lshr_b32 s1, s0, 6
	s_and_b32 s1, s1, 12
	s_add_i32 s1, s1, s78
	s_andn2_b32 s4, 15, s1
	s_lshl_b32 s46, s4, 3
	v_readlane_b32 s66, v254, 16
	s_lshr_b32 s69, s0, 8
	s_add_i32 s79, s46, s66
	s_lshl_b32 s0, s69, 12
	s_lshl_b32 s66, s79, 5
	s_add_i32 s66, s66, s0
	s_lshl_b32 s1, s78, 3
	v_or_b32_e32 v2, s66, v165
	s_and_b32 s1, s1, 0x780
	v_lshlrev_b64 v[4:5], 12, v[2:3]
	v_lshl_add_u64 v[4:5], s[48:49], 0, v[4:5]
	s_lshl_b32 s0, s1, 1
	s_mov_b32 s1, s77
	v_lshl_add_u64 v[4:5], v[4:5], 0, s[0:1]
	v_mov_b32_e32 v173, v3
	v_lshl_add_u64 v[4:5], v[4:5], 0, v[172:173]
	global_load_dwordx4 v[132:135], v[4:5], off
	global_load_dwordx4 v[136:139], v[4:5], off offset:32
	global_load_dwordx4 v[140:143], v[4:5], off offset:64
	global_load_dwordx4 v[144:147], v[4:5], off offset:96
	global_load_dwordx4 v[148:151], v[4:5], off offset:128
	global_load_dwordx4 v[152:155], v[4:5], off offset:160
	global_load_dwordx4 v[156:159], v[4:5], off offset:192
	global_load_dwordx4 v[160:163], v[4:5], off offset:224
	s_mov_b64 s[86:87], exec
	v_readlane_b32 s66, v254, 39
	v_readlane_b32 s67, v254, 40
	s_and_b64 s[66:67], s[86:87], s[66:67]
	s_mov_b64 exec, s[66:67]
	ds_write_b32 v199, v3
	s_or_b64 exec, exec, s[86:87]
	s_lshl_b32 s1, s69, 24
	v_readlane_b32 s66, v254, 28
	v_readlane_b32 s67, v254, 29
	s_add_u32 s69, s66, s1
	s_addc_u32 s76, s67, 0
	s_add_u32 s1, s50, s1
	s_addc_u32 s67, s51, 0
	s_add_u32 s66, s1, s0
	s_addc_u32 s67, s67, 0
	s_add_u32 s86, s69, s0
	s_addc_u32 s87, s76, 0
	s_lshl_b32 s1, s46, 17
	v_lshl_add_u64 v[4:5], s[66:67], 0, v[168:169]
	v_lshlrev_b32_e32 v6, 1, v164
	v_mov_b32_e32 v7, v3
	v_lshl_add_u64 v[174:175], v[4:5], 0, v[6:7]
	v_lshl_add_u64 v[4:5], s[86:87], 0, v[168:169]
	s_or_b32 s76, s1, 0xe0000
	s_mov_b32 m0, s94
	v_lshl_add_u64 v[176:177], v[4:5], 0, v[6:7]
	v_lshl_add_u64 v[4:5], v[174:175], 0, s[76:77]
	s_lshl_b32 s4, s4, 20
	global_load_lds_dwordx4 v[4:5], off
	v_lshl_add_u64 v[4:5], v[176:177], 0, s[76:77]
	s_mov_b32 m0, s56
	s_or_b32 s76, s4, 0xc0000
	global_load_lds_dwordx4 v[4:5], off
	v_lshl_add_u64 v[4:5], v[174:175], 0, s[76:77]
	s_mov_b32 m0, s57
	v_readlane_b32 s66, v254, 0
	global_load_lds_dwordx4 v[4:5], off
	v_lshl_add_u64 v[4:5], v[176:177], 0, s[76:77]
	s_mov_b32 m0, s89
	s_or_b32 s76, s4, 0xa0000
	global_load_lds_dwordx4 v[4:5], off
	v_lshl_add_u64 v[4:5], v[174:175], 0, s[76:77]
	s_mov_b32 m0, s93
	v_readlane_b32 s67, v254, 1
	global_load_lds_dwordx4 v[4:5], off
	v_lshl_add_u64 v[4:5], v[176:177], 0, s[76:77]
	s_mov_b32 m0, s68
	s_add_i32 s76, s1, 0x80000
	global_load_lds_dwordx4 v[4:5], off
	s_waitcnt vmcnt(4)
	v_readlane_b32 s1, v254, 42
	s_waitcnt lgkmcnt(0)
	s_barrier
	v_lshl_add_u64 v[4:5], v[174:175], 0, s[76:77]
	s_mov_b32 m0, s1
	v_readlane_b32 s1, v254, 43
	global_load_lds_dwordx4 v[4:5], off
	v_lshl_add_u64 v[4:5], v[176:177], 0, s[76:77]
	s_mov_b32 m0, s1
	s_andn2_b64 vcc, exec, s[66:67]
	global_load_lds_dwordx4 v[4:5], off
	s_cbranch_vccnz .LBB0_383
	v_add_u32_e32 v1, v197, v183
	ds_read_b128 v[4:7], v1
	v_add_u32_e32 v1, v197, v184
	ds_read_b128 v[20:23], v1
	v_add_u32_e32 v1, v197, v185
	s_andn2_b64 vcc, exec, s[82:83]
	s_waitcnt vmcnt(0) lgkmcnt(0)
	v_mfma_f32_32x32x16_bf16 v[4:19], v[4:7], v[132:135], 0
	v_mfma_f32_32x32x16_bf16 v[4:19], v[20:23], v[136:139], v[4:19]
	ds_read_b128 v[20:23], v1
	v_add_u32_e32 v1, v197, v186
	ds_read_b128 v[24:27], v1
	v_add_u32_e32 v1, v197, v187
	s_waitcnt lgkmcnt(1)
	v_mfma_f32_32x32x16_bf16 v[4:19], v[20:23], v[140:143], v[4:19]
	ds_read_b128 v[20:23], v1
	v_add_u32_e32 v1, v197, v188
	s_waitcnt lgkmcnt(1)
	v_mfma_f32_32x32x16_bf16 v[4:19], v[24:27], v[144:147], v[4:19]
	ds_read_b128 v[24:27], v1
	v_add_u32_e32 v1, v197, v189
	s_waitcnt lgkmcnt(1)
	v_mfma_f32_32x32x16_bf16 v[4:19], v[20:23], v[148:151], v[4:19]
	ds_read_b128 v[20:23], v1
	v_add_u32_e32 v1, v197, v190
	s_waitcnt lgkmcnt(1)
	v_mfma_f32_32x32x16_bf16 v[4:19], v[24:27], v[152:155], v[4:19]
	ds_read_b128 v[24:27], v1
	s_waitcnt lgkmcnt(1)
	v_mfma_f32_32x32x16_bf16 v[4:19], v[20:23], v[156:159], v[4:19]
	s_waitcnt lgkmcnt(0)
	v_mfma_f32_32x32x16_bf16 v[4:19], v[24:27], v[160:163], v[4:19]
	s_nop 11
	v_exp_f32_e64 v1, -|v4|
	v_exp_f32_e64 v21, -|v5|
	v_exp_f32_e64 v23, -|v6|
	v_exp_f32_e64 v27, -|v8|
	v_exp_f32_e64 v25, -|v7|
	v_exp_f32_e64 v29, -|v9|
	v_add_f32_e32 v1, 1.0, v1
	v_exp_f32_e64 v31, -|v10|
	v_add_f32_e32 v21, 1.0, v21
	v_add_f32_e32 v23, 1.0, v23
	v_add_f32_e32 v27, 1.0, v27
	v_log_f32_e32 v1, v1
	v_log_f32_e32 v21, v21
	v_log_f32_e32 v23, v23
	v_log_f32_e32 v27, v27
	v_exp_f32_e64 v33, -|v11|
	v_add_f32_e32 v25, 1.0, v25
	v_add_f32_e32 v29, 1.0, v29
	v_max_f32_e32 v20, 0, v4
	v_log_f32_e32 v25, v25
	v_log_f32_e32 v29, v29
	v_max_f32_e32 v22, 0, v5
	v_max_f32_e32 v24, 0, v6
	v_max_f32_e32 v28, 0, v8
	v_add_f32_e32 v31, 1.0, v31
	v_add_f32_e32 v1, v20, v1
	v_log_f32_e32 v31, v31
	v_add_f32_e32 v20, v22, v21
	v_add_f32_e32 v21, v24, v23
	v_add_f32_e32 v23, v28, v27
	v_cndmask_b32_e64 v27, 0, -v1, s[10:11]
	v_max_f32_e32 v26, 0, v7
	v_max_f32_e32 v30, 0, v9
	v_add_f32_e32 v33, 1.0, v33
	v_cndmask_b32_e64 v28, 0, -v20, s[12:13]
	v_cndmask_b32_e64 v27, -v1, v27, s[82:83]
	v_log_f32_e32 v33, v33
	v_add_f32_e32 v22, v26, v25
	v_add_f32_e32 v24, v30, v29
	v_cndmask_b32_e64 v29, 0, -v21, s[14:15]
	v_cndmask_b32_e64 v28, -v20, v28, s[82:83]
	v_add_f32_e32 v1, 0, v27
	v_max_f32_e32 v32, 0, v10
	v_cndmask_b32_e64 v30, 0, -v22, s[16:17]
	v_cndmask_b32_e64 v29, -v21, v29, s[82:83]
	v_add_f32_e32 v1, v28, v1
	v_exp_f32_e64 v35, -|v12|
	v_add_f32_e32 v25, v32, v31
	v_cndmask_b32_e64 v31, 0, -v23, s[18:19]
	v_cndmask_b32_e64 v30, -v22, v30, s[82:83]
	v_add_f32_e32 v1, v29, v1
	v_max_f32_e32 v34, 0, v11
	v_cndmask_b32_e64 v32, 0, -v24, s[20:21]
	v_cndmask_b32_e64 v31, -v23, v31, s[82:83]
	v_add_f32_e32 v1, v30, v1
	v_add_f32_e32 v26, v34, v33
	v_cndmask_b32_e64 v32, -v24, v32, s[82:83]
	v_add_f32_e32 v1, v31, v1
	v_add_f32_e32 v22, v32, v1
	v_cndmask_b32_e64 v1, 0, -v26, s[24:25]
	v_cndmask_b32_e64 v26, -v26, v1, s[82:83]
	v_add_f32_e32 v1, 1.0, v35
	v_log_f32_e32 v1, v1
	v_exp_f32_e64 v21, -|v13|
	v_max_f32_e32 v20, 0, v12
	v_add_f32_e32 v1, v20, v1
	v_cndmask_b32_e64 v20, 0, -v1, s[26:27]
	v_cndmask_b32_e64 v23, -v1, v20, s[82:83]
	v_add_f32_e32 v1, 1.0, v21
	v_log_f32_e32 v1, v1
	v_max_f32_e32 v21, 0, v13
	v_add_f32_e32 v20, 0, v23
	v_add_f32_e32 v1, v21, v1
	v_exp_f32_e64 v21, -|v14|
	v_cndmask_b32_e64 v24, 0, -v1, s[28:29]
	v_cndmask_b32_e64 v24, -v1, v24, s[82:83]
	v_add_f32_e32 v1, v24, v20
	v_add_f32_e32 v20, 1.0, v21
	v_log_f32_e32 v20, v20
	v_exp_f32_e64 v34, -|v15|
	v_max_f32_e32 v21, 0, v14
	v_add_f32_e32 v20, v21, v20
	v_cndmask_b32_e64 v21, 0, -v20, s[30:31]
	v_cndmask_b32_e64 v35, -v20, v21, s[82:83]
	v_add_f32_e32 v20, 1.0, v34
	v_log_f32_e32 v20, v20
	v_max_f32_e32 v21, 0, v15
	v_exp_f32_e64 v36, -|v17|
	v_add_f32_e32 v20, v21, v20
	v_exp_f32_e64 v21, -|v16|
	v_cndmask_b32_e64 v34, 0, -v20, s[34:35]
	v_cndmask_b32_e64 v34, -v20, v34, s[82:83]
	v_exp_f32_e64 v38, -|v19|
	v_add_f32_e32 v20, 1.0, v21
	v_log_f32_e32 v20, v20
	v_max_f32_e32 v21, 0, v16
	v_add_f32_e32 v1, v35, v1
	v_add_f32_e32 v20, v21, v20
	v_cndmask_b32_e64 v21, 0, -v20, s[36:37]
	v_cndmask_b32_e64 v37, -v20, v21, s[82:83]
	v_add_f32_e32 v20, 1.0, v36
	v_log_f32_e32 v20, v20
	v_max_f32_e32 v21, 0, v17
	v_add_f32_e32 v1, v34, v1
	v_add_f32_e32 v20, v21, v20
	v_exp_f32_e64 v21, -|v18|
	v_cndmask_b32_e64 v36, 0, -v20, s[38:39]
	v_cndmask_b32_e64 v36, -v20, v36, s[82:83]
	v_add_f32_e32 v1, v37, v1
	v_add_f32_e32 v20, 1.0, v21
	v_log_f32_e32 v20, v20
	v_max_f32_e32 v21, 0, v18
	v_add_f32_e32 v1, v36, v1
	v_add_f32_e32 v20, v21, v20
	v_cndmask_b32_e64 v21, 0, -v20, s[40:41]
	v_cndmask_b32_e64 v39, -v20, v21, s[82:83]
	v_add_f32_e32 v20, 1.0, v38
	v_log_f32_e32 v20, v20
	v_max_f32_e32 v21, 0, v19
	v_add_f32_e32 v1, v39, v1
	v_add_f32_e32 v20, v21, v20
	v_cndmask_b32_e64 v21, 0, -v20, s[42:43]
	v_cndmask_b32_e64 v38, -v20, v21, s[82:83]
	v_add_f32_e32 v20, v38, v1
	v_mov_b32_e32 v1, v20
	v_mov_b32_e32 v21, v20
	s_nop 1
	v_permlane32_swap_b32_e32 v1, v21
	v_cndmask_b32_e64 v21, v1, v21, s[2:3]
	v_add_f32_e32 v1, 0, v21
	v_cndmask_b32_e64 v40, 0, v1, s[6:7]
	v_add_f32_e32 v42, v1, v20
	v_add_f32_e32 v1, v19, v38
	v_add_f32_e32 v19, v40, v38
	v_add_f32_e32 v18, v18, v39
	v_add_f32_e32 v18, v19, v18
	v_add_f32_e32 v19, v39, v19
	v_add_f32_e32 v17, v17, v36
	v_add_f32_e32 v17, v17, v19
	v_add_f32_e32 v19, v36, v19
	v_add_f32_e32 v16, v16, v37
	v_add_f32_e32 v16, v16, v19
	v_add_f32_e32 v19, v37, v19
	v_add_f32_e32 v15, v15, v34
	v_add_f32_e32 v15, v15, v19
	v_add_f32_e32 v19, v34, v19
	v_add_f32_e32 v14, v14, v35
	v_cndmask_b32_e64 v33, 0, -v25, s[22:23]
	v_add_f32_e32 v14, v14, v19
	v_add_f32_e32 v19, v35, v19
	v_add_f32_e32 v13, v13, v24
	v_add_f32_e32 v13, v13, v19
	v_add_f32_e32 v19, v24, v19
	v_cndmask_b32_e64 v24, -v25, v33, s[82:83]
	v_add_f32_e32 v22, v24, v22
	v_add_f32_e32 v22, v26, v22
	v_add_f32_e32 v12, v12, v23
	v_mov_b32_e32 v23, v22
	v_mov_b32_e32 v25, v22
	s_nop 1
	v_permlane32_swap_b32_e32 v23, v25
	v_add_f32_e32 v41, 0, v20
	v_cndmask_b32_e64 v23, v23, v25, s[2:3]
	v_add_f32_e32 v12, v12, v19
	v_add_f32_e32 v19, v41, v21
	v_add_f32_e32 v25, v42, v23
	v_add_f32_e32 v11, v11, v26
	v_cndmask_b32_e64 v25, v19, v25, s[6:7]
	v_add_f32_e32 v11, v11, v25
	v_exp_f32_e32 v19, v11
	v_mov_b32_e32 v11, v26
	v_pk_add_f32 v[10:11], v[10:11], v[24:25]
	v_add_f32_e32 v9, v9, v32
	v_add_f32_e32 v10, v10, v11
	v_add_f32_e32 v11, v24, v11
	v_add_f32_e32 v9, v9, v11
	v_add_f32_e32 v11, v32, v11
	v_add_f32_e32 v8, v8, v31
	v_add_f32_e32 v8, v8, v11
	v_add_f32_e32 v11, v31, v11
	v_add_f32_e32 v7, v7, v30
	v_add_f32_e32 v7, v7, v11
	v_add_f32_e32 v11, v30, v11
	v_add_f32_e32 v6, v6, v29
	v_add_f32_e32 v6, v6, v11
	v_add_f32_e32 v11, v29, v11
	v_add_f32_e32 v5, v5, v28
	v_add_f32_e32 v5, v5, v11
	v_add_f32_e32 v11, v28, v11
	v_add_f32_e32 v4, v4, v27
	v_add_f32_e32 v1, v40, v1
	v_add_f32_e32 v4, v4, v11
	v_exp_f32_e32 v1, v1
	v_exp_f32_e32 v18, v18
	v_exp_f32_e32 v17, v17
	v_exp_f32_e32 v16, v16
	v_exp_f32_e32 v15, v15
	v_exp_f32_e32 v14, v14
	v_exp_f32_e32 v13, v13
	v_exp_f32_e32 v12, v12
	v_exp_f32_e32 v10, v10
	v_exp_f32_e32 v9, v9
	v_exp_f32_e32 v8, v8
	v_exp_f32_e32 v7, v7
	v_exp_f32_e32 v6, v6
	v_exp_f32_e32 v5, v5
	v_exp_f32_e32 v4, v4
	s_cbranch_vccnz .LBB0_382
	s_or_b64 vcc, s[12:13], s[10:11]
	v_cndmask_b32_e32 v4, 0, v4, vcc
	s_or_b64 vcc, s[16:17], s[14:15]
	v_cndmask_b32_e32 v6, 0, v6, vcc
	s_or_b64 vcc, s[20:21], s[18:19]
	v_cndmask_b32_e32 v8, 0, v8, vcc
	s_or_b64 vcc, s[24:25], s[22:23]
	v_cndmask_b32_e32 v10, 0, v10, vcc
	s_or_b64 vcc, s[28:29], s[26:27]
	v_cndmask_b32_e32 v12, 0, v12, vcc
	s_or_b64 vcc, s[34:35], s[30:31]
	v_cndmask_b32_e32 v14, 0, v14, vcc
	s_or_b64 vcc, s[38:39], s[36:37]
	v_cndmask_b32_e32 v16, 0, v16, vcc
	s_or_b64 vcc, s[42:43], s[40:41]
	v_cndmask_b32_e64 v5, 0, v5, s[12:13]
	v_cndmask_b32_e64 v7, 0, v7, s[16:17]
	v_cndmask_b32_e64 v9, 0, v9, s[20:21]
	v_cndmask_b32_e64 v19, 0, v19, s[24:25]
	v_cndmask_b32_e64 v13, 0, v13, s[28:29]
	v_cndmask_b32_e64 v15, 0, v15, s[34:35]
	v_cndmask_b32_e64 v17, 0, v17, s[38:39]
	v_cndmask_b32_e64 v1, 0, v1, s[42:43]
	v_cndmask_b32_e32 v18, 0, v18, vcc

.LBB0_388:
	s_and_b32 s46, s69, 8
	s_xor_b32 s66, s46, 8
	s_add_i32 s67, 0, 0x10000
	s_lshl_b32 s66, s66, 2
	s_add_i32 s66, s67, s66
	v_mov_b32_e32 v1, s66
	s_xor_b32 s66, s46, 9
	s_lshl_b32 s66, s66, 2
	s_waitcnt vmcnt(4)
	s_add_i32 s66, s67, s66
	s_waitcnt lgkmcnt(0)
	s_barrier
	v_mov_b32_e32 v2, s66
	s_xor_b32 s66, s46, 10
	ds_read_b32 v1, v1
	ds_read_b32 v2, v2
	s_lshl_b32 s66, s66, 2
	s_add_i32 s66, s67, s66
	v_mov_b32_e32 v228, s66
	s_xor_b32 s66, s46, 11
	ds_read_b32 v68, v228
	s_lshl_b32 s66, s66, 2
	s_add_i32 s66, s67, s66
	s_waitcnt lgkmcnt(0)
	v_and_b32_e32 v1, v1, v2
	v_mov_b32_e32 v2, s66
	s_xor_b32 s66, s46, 12
	s_lshl_b32 s66, s66, 2
	s_add_i32 s66, s67, s66
	v_and_b32_e32 v1, v1, v68
	v_mov_b32_e32 v68, s66
	s_xor_b32 s66, s46, 13
	s_lshl_b32 s66, s66, 2
	s_add_i32 s66, s67, s66
	v_mov_b32_e32 v69, s66
	s_xor_b32 s66, s46, 14
	s_lshl_b32 s66, s66, 2
	s_add_i32 s66, s67, s66
	ds_read_b32 v2, v2
	v_mov_b32_e32 v70, s66
	s_xor_b32 s66, s46, 15
	ds_read_b32 v68, v68
	s_lshl_b32 s66, s66, 2
	ds_read_b32 v69, v69
	s_add_i32 s66, s67, s66
	ds_read_b32 v70, v70
	v_mov_b32_e32 v71, s66
	ds_read_b32 v71, v71
	s_waitcnt lgkmcnt(0)
	v_and_b32_e32 v1, v1, v2
	s_waitcnt lgkmcnt(3)
	v_and_b32_e32 v1, v1, v68
	s_waitcnt lgkmcnt(2)
	v_and_b32_e32 v1, v1, v69
	s_waitcnt lgkmcnt(1)
	v_and_b32_e32 v1, v1, v70
	s_waitcnt lgkmcnt(0)
	v_and_b32_e32 v1, v1, v71
	v_and_b32_e32 v1, 1, v1
	v_cmp_eq_u32_e32 vcc, 1, v1
	s_mov_b64 s[90:91], -1
	s_and_b64 vcc, exec, vcc
	s_cbranch_vccnz .LBB0_387
	s_max_i32 s66, s1, 3
	s_lshl_b32 s66, s66, 5
	s_addk_i32 s66, 0xffa0
	s_and_b32 s90, s4, 0xc000
	s_ashr_i32 s67, s66, 31
	s_lshl_b64 s[66:67], s[66:67], 12
	s_add_i32 s90, s94, s90
	v_lshl_add_u64 v[68:69], v[174:175], 0, s[66:67]
	s_mov_b32 m0, s90
	s_nop 0
	global_load_lds_dwordx4 v[68:69], off
	v_lshl_add_u64 v[68:69], v[176:177], 0, s[66:67]
	s_add_i32 m0, s90, 0x2000
	s_cmp_gt_i32 s1, s79
	global_load_lds_dwordx4 v[68:69], off
	s_cselect_b64 s[66:67], -1, 0
	s_or_b64 s[66:67], s[66:67], s[86:87]
	s_and_b64 vcc, exec, s[66:67]
	s_cbranch_vccnz .LBB0_394
	s_add_i32 s66, s4, 0xffff4000
	s_and_b32 s66, s66, 0xc000
	s_add_i32 s90, s66, 0
	v_add_u32_e32 v1, s90, v181
	v_add_u32_e32 v2, v1, v183
	ds_read_b128 v[68:71], v2
	v_add_u32_e32 v2, v1, v184
	ds_read_b128 v[84:87], v2
	v_add_u32_e32 v2, v1, v185
	s_cmp_eq_u32 s76, 0
	s_cselect_b64 s[86:87], -1, 0
	s_cmp_lg_u32 s76, 0
	s_waitcnt lgkmcnt(0)
	v_mfma_f32_32x32x16_bf16 v[68:83], v[68:71], v[132:135], 0
	v_mfma_f32_32x32x16_bf16 v[68:83], v[84:87], v[136:139], v[68:83]
	ds_read_b128 v[84:87], v2
	v_add_u32_e32 v2, v1, v186
	ds_read_b128 v[88:91], v2
	v_add_u32_e32 v2, v1, v187
	s_waitcnt lgkmcnt(0)
	v_mfma_f32_32x32x16_bf16 v[68:83], v[84:87], v[140:143], v[68:83]
	ds_read_b128 v[84:87], v2
	v_add_u32_e32 v2, v1, v188
	v_mfma_f32_32x32x16_bf16 v[68:83], v[88:91], v[144:147], v[68:83]
	ds_read_b128 v[88:91], v2
	v_add_u32_e32 v2, v1, v189
	v_add_u32_e32 v1, v1, v190
	s_waitcnt lgkmcnt(0)
	v_mfma_f32_32x32x16_bf16 v[68:83], v[84:87], v[148:151], v[68:83]
	ds_read_b128 v[84:87], v2
	v_mfma_f32_32x32x16_bf16 v[68:83], v[88:91], v[152:155], v[68:83]
	ds_read_b128 v[88:91], v1
	s_waitcnt lgkmcnt(0)
	v_mfma_f32_32x32x16_bf16 v[68:83], v[84:87], v[156:159], v[68:83]
	v_mfma_f32_32x32x16_bf16 v[68:83], v[88:91], v[160:163], v[68:83]
	s_nop 11
	v_exp_f32_e64 v1, -|v68|
	v_exp_f32_e64 v84, -|v69|
	v_exp_f32_e64 v88, -|v71|
	v_exp_f32_e64 v86, -|v70|
	v_exp_f32_e64 v90, -|v72|
	v_exp_f32_e64 v92, -|v73|
	v_add_f32_e32 v1, 1.0, v1
	v_add_f32_e32 v84, 1.0, v84
	v_add_f32_e32 v88, 1.0, v88
	v_log_f32_e32 v1, v1
	v_exp_f32_e64 v94, -|v74|
	v_add_f32_e32 v86, 1.0, v86
	v_add_f32_e32 v90, 1.0, v90
	v_log_f32_e32 v84, v84
	v_log_f32_e32 v88, v88
	v_log_f32_e32 v86, v86
	v_log_f32_e32 v90, v90
	v_max_f32_e32 v2, 0, v68
	v_add_f32_e32 v92, 1.0, v92
	v_max_f32_e32 v85, 0, v69
	v_max_f32_e32 v89, 0, v71
	v_log_f32_e32 v92, v92
	v_add_f32_e32 v1, v2, v1
	v_max_f32_e32 v87, 0, v70
	v_max_f32_e32 v91, 0, v72
	v_add_f32_e32 v94, 1.0, v94
	v_add_f32_e32 v2, v85, v84
	v_add_f32_e32 v85, v89, v88
	v_cndmask_b32_e64 v89, 0, -v1, s[10:11]
	v_log_f32_e32 v94, v94
	v_add_f32_e32 v84, v87, v86
	v_add_f32_e32 v86, v91, v90
	v_cndmask_b32_e64 v90, 0, -v2, s[12:13]
	v_cndmask_b32_e64 v98, -v1, v89, s[86:87]
	v_max_f32_e32 v93, 0, v73
	v_cndmask_b32_e64 v91, 0, -v84, s[14:15]
	v_cndmask_b32_e64 v90, -v2, v90, s[86:87]
	v_add_f32_e32 v1, 0, v98
	v_exp_f32_e64 v96, -|v75|
	v_add_f32_e32 v87, v93, v92
	v_cndmask_b32_e64 v92, 0, -v85, s[16:17]
	v_cndmask_b32_e64 v91, -v84, v91, s[86:87]
	v_add_f32_e32 v1, v90, v1
	v_max_f32_e32 v95, 0, v74
	v_cndmask_b32_e64 v93, 0, -v86, s[18:19]
	v_cndmask_b32_e64 v92, -v85, v92, s[86:87]
	v_add_f32_e32 v1, v91, v1
	v_add_f32_e32 v88, v95, v94
	v_cndmask_b32_e64 v94, 0, -v87, s[20:21]
	v_cndmask_b32_e64 v93, -v86, v93, s[86:87]
	v_add_f32_e32 v1, v92, v1
	v_cndmask_b32_e64 v87, -v87, v94, s[86:87]
	v_add_f32_e32 v1, v93, v1
	v_add_f32_e32 v96, 1.0, v96
	v_add_f32_e32 v86, v87, v1
	v_exp_f32_e64 v1, -|v76|
	v_log_f32_e32 v96, v96
	v_max_f32_e32 v97, 0, v75
	v_add_f32_e32 v1, 1.0, v1
	v_add_f32_e32 v2, v97, v96
	v_log_f32_e32 v1, v1
	v_cndmask_b32_e64 v84, 0, -v2, s[24:25]
	v_cndmask_b32_e64 v94, -v2, v84, s[86:87]
	v_exp_f32_e64 v84, -|v77|
	v_max_f32_e32 v2, 0, v76
	v_add_f32_e32 v1, v2, v1
	v_cndmask_b32_e64 v2, 0, -v1, s[26:27]
	v_cndmask_b32_e64 v89, -v1, v2, s[86:87]
	v_add_f32_e32 v1, 1.0, v84
	v_log_f32_e32 v1, v1
	v_max_f32_e32 v84, 0, v77
	v_add_f32_e32 v2, 0, v89
	v_add_f32_e32 v1, v84, v1
	v_exp_f32_e64 v84, -|v78|
	v_cndmask_b32_e64 v85, 0, -v1, s[28:29]
	v_cndmask_b32_e64 v96, -v1, v85, s[86:87]
	v_add_f32_e32 v1, v96, v2
	v_add_f32_e32 v2, 1.0, v84
	v_log_f32_e32 v2, v2
	v_exp_f32_e64 v85, -|v79|
	v_max_f32_e32 v84, 0, v78
	v_add_f32_e32 v2, v84, v2
	v_cndmask_b32_e64 v84, 0, -v2, s[30:31]
	v_cndmask_b32_e64 v97, -v2, v84, s[86:87]
	v_add_f32_e32 v2, 1.0, v85
	v_log_f32_e32 v2, v2
	v_max_f32_e32 v84, 0, v79
	v_add_f32_e32 v1, v97, v1
	v_add_f32_e32 v2, v84, v2
	v_exp_f32_e64 v84, -|v80|
	v_cndmask_b32_e64 v85, 0, -v2, s[34:35]
	v_cndmask_b32_e64 v99, -v2, v85, s[86:87]
	v_exp_f32_e64 v85, -|v81|
	v_add_f32_e32 v2, 1.0, v84
	v_log_f32_e32 v2, v2
	v_max_f32_e32 v84, 0, v80
	v_add_f32_e32 v1, v99, v1
	v_add_f32_e32 v2, v84, v2
	v_cndmask_b32_e64 v84, 0, -v2, s[36:37]
	v_cndmask_b32_e64 v100, -v2, v84, s[86:87]
	v_add_f32_e32 v2, 1.0, v85
	v_log_f32_e32 v2, v2
	v_max_f32_e32 v84, 0, v81
	v_add_f32_e32 v1, v100, v1
	v_add_f32_e32 v2, v84, v2
	v_exp_f32_e64 v84, -|v82|
	v_cndmask_b32_e64 v85, 0, -v2, s[38:39]
	v_cndmask_b32_e64 v101, -v2, v85, s[86:87]
	v_exp_f32_e64 v85, -|v83|
	v_add_f32_e32 v2, 1.0, v84
	v_log_f32_e32 v2, v2
	v_max_f32_e32 v84, 0, v82
	v_add_f32_e32 v1, v101, v1
	v_add_f32_e32 v2, v84, v2
	v_cndmask_b32_e64 v84, 0, -v2, s[40:41]
	v_cndmask_b32_e64 v102, -v2, v84, s[86:87]
	v_add_f32_e32 v2, 1.0, v85
	v_log_f32_e32 v2, v2
	v_max_f32_e32 v84, 0, v83
	v_add_f32_e32 v1, v102, v1
	v_add_f32_e32 v2, v84, v2
	v_cndmask_b32_e64 v84, 0, -v2, s[42:43]
	v_cndmask_b32_e64 v2, -v2, v84, s[86:87]
	v_add_f32_e32 v84, v2, v1
	v_mov_b32_e32 v1, v84
	v_mov_b32_e32 v85, v84
	s_nop 1
	v_permlane32_swap_b32_e32 v1, v85
	v_cndmask_b32_e64 v85, v1, v85, s[2:3]
	v_add_f32_e32 v1, v173, v85
	v_cndmask_b32_e64 v103, v173, v1, s[6:7]
	v_add_f32_e32 v105, v1, v84
	v_add_f32_e32 v1, v83, v2
	v_add_f32_e32 v83, v103, v2
	v_add_f32_e32 v2, v82, v102
	v_add_f32_e32 v82, v102, v83
	v_add_f32_e32 v81, v81, v101
	v_add_f32_e32 v81, v81, v82
	v_add_f32_e32 v82, v101, v82
	v_add_f32_e32 v80, v80, v100
	v_add_f32_e32 v80, v80, v82
	v_add_f32_e32 v82, v100, v82
	v_add_f32_e32 v79, v79, v99
	v_add_f32_e32 v79, v79, v82
	v_add_f32_e32 v82, v99, v82
	v_add_f32_e32 v78, v78, v97
	v_cndmask_b32_e64 v95, 0, -v88, s[22:23]
	v_add_f32_e32 v78, v78, v82
	v_add_f32_e32 v82, v97, v82
	v_add_f32_e32 v77, v77, v96
	v_add_f32_e32 v77, v77, v82
	v_add_f32_e32 v82, v96, v82
	v_add_f32_e32 v76, v76, v89
	v_cndmask_b32_e64 v88, -v88, v95, s[86:87]
	v_add_f32_e32 v76, v76, v82
	v_add_f32_e32 v82, v88, v86
	v_add_f32_e32 v82, v94, v82
	v_mov_b32_e32 v86, v82
	v_mov_b32_e32 v89, v82
	s_nop 1
	v_permlane32_swap_b32_e32 v86, v89
	v_add_f32_e32 v104, v173, v84
	v_cndmask_b32_e64 v86, v86, v89, s[2:3]
	v_add_f32_e32 v2, v83, v2
	v_add_f32_e32 v83, v104, v85
	v_add_f32_e32 v89, v105, v86
	v_add_f32_e32 v75, v75, v94
	v_cndmask_b32_e64 v89, v83, v89, s[6:7]
	v_add_f32_e32 v75, v75, v89
	v_exp_f32_e32 v83, v75
	v_mov_b32_e32 v75, v94
	v_pk_add_f32 v[74:75], v[74:75], v[88:89]
	v_add_f32_e32 v73, v73, v87
	v_add_f32_e32 v74, v74, v75
	v_add_f32_e32 v75, v88, v75
	v_add_f32_e32 v73, v73, v75
	v_add_f32_e32 v75, v87, v75
	v_add_f32_e32 v72, v72, v93
	v_add_f32_e32 v72, v72, v75
	v_add_f32_e32 v75, v93, v75
	v_add_f32_e32 v71, v71, v92
	v_add_f32_e32 v71, v71, v75
	v_add_f32_e32 v75, v92, v75
	v_add_f32_e32 v70, v70, v91
	v_add_f32_e32 v70, v70, v75
	v_add_f32_e32 v75, v91, v75
	v_add_f32_e32 v69, v69, v90
	v_add_f32_e32 v69, v69, v75
	v_add_f32_e32 v75, v90, v75
	v_add_f32_e32 v68, v68, v98
	v_add_f32_e32 v1, v103, v1
	v_add_f32_e32 v68, v68, v75
	v_exp_f32_e32 v1, v1
	v_exp_f32_e32 v2, v2
	v_exp_f32_e32 v81, v81
	v_exp_f32_e32 v80, v80
	v_exp_f32_e32 v79, v79
	v_exp_f32_e32 v78, v78
	v_exp_f32_e32 v77, v77
	v_exp_f32_e32 v76, v76
	v_exp_f32_e32 v74, v74
	v_exp_f32_e32 v73, v73
	v_exp_f32_e32 v72, v72
	v_exp_f32_e32 v71, v71
	v_exp_f32_e32 v70, v70
	v_exp_f32_e32 v69, v69
	v_exp_f32_e32 v68, v68
	s_cbranch_scc1 .LBB0_392
	s_or_b64 vcc, s[12:13], s[10:11]
	v_cndmask_b32_e32 v68, 0, v68, vcc
	s_or_b64 vcc, s[16:17], s[14:15]
	v_cndmask_b32_e32 v70, 0, v70, vcc
	s_or_b64 vcc, s[20:21], s[18:19]
	v_cndmask_b32_e32 v72, 0, v72, vcc
	s_or_b64 vcc, s[24:25], s[22:23]
	v_cndmask_b32_e32 v74, 0, v74, vcc
	s_or_b64 vcc, s[28:29], s[26:27]
	v_cndmask_b32_e32 v76, 0, v76, vcc
	s_or_b64 vcc, s[34:35], s[30:31]
	v_cndmask_b32_e32 v78, 0, v78, vcc
	s_or_b64 vcc, s[38:39], s[36:37]
	v_cndmask_b32_e32 v80, 0, v80, vcc
	s_or_b64 vcc, s[42:43], s[40:41]
	v_cndmask_b32_e64 v69, 0, v69, s[12:13]
	v_cndmask_b32_e64 v71, 0, v71, s[16:17]
	v_cndmask_b32_e64 v73, 0, v73, s[20:21]
	v_cndmask_b32_e64 v83, 0, v83, s[24:25]
	v_cndmask_b32_e64 v77, 0, v77, s[28:29]
	v_cndmask_b32_e64 v79, 0, v79, s[34:35]
	v_cndmask_b32_e64 v81, 0, v81, s[38:39]
	v_cndmask_b32_e64 v1, 0, v1, s[42:43]
	v_cndmask_b32_e32 v2, 0, v2, vcc

.LBB0_401:
	ds_read_b64_tr_b16 v[226:227], v242 offset:12288
	ds_read_b64_tr_b16 v[228:229], v243 offset:13312
	ds_read_b64_tr_b16 v[230:231], v244 offset:12288
	ds_read_b64_tr_b16 v[232:233], v245 offset:12288
	ds_read_b64_tr_b16 v[234:235], v246 offset:12288
	ds_read_b64_tr_b16 v[236:237], v247 offset:12288
	ds_read_b64_tr_b16 v[238:239], v248 offset:12288
	ds_read_b64_tr_b16 v[240:241], v249 offset:12288
	v_sub_f32_e32 v5, v82, v8
	v_sub_f32_e32 v7, v83, v8
	v_sub_f32_e32 v9, v84, v8
	v_sub_f32_e32 v11, v85, v8
	v_sub_f32_e32 v12, v86, v8
	v_sub_f32_e32 v13, v87, v8
	v_sub_f32_e32 v14, v88, v8
	v_sub_f32_e32 v15, v89, v8
	v_sub_f32_e32 v16, v90, v8
	v_sub_f32_e32 v17, v91, v8
	v_sub_f32_e32 v82, v92, v8
	v_sub_f32_e32 v83, v93, v8
	v_sub_f32_e32 v84, v94, v8
	v_sub_f32_e32 v85, v95, v8
	v_sub_f32_e32 v86, v96, v8
	v_sub_f32_e32 v87, v97, v8
	v_exp_f32_e32 v5, v5
	v_exp_f32_e32 v7, v7
	v_exp_f32_e32 v9, v9
	v_exp_f32_e32 v11, v11
	v_exp_f32_e32 v12, v12
	v_exp_f32_e32 v13, v13
	v_exp_f32_e32 v14, v14
	v_exp_f32_e32 v15, v15
	v_exp_f32_e32 v16, v16
	v_exp_f32_e32 v17, v17
	v_exp_f32_e32 v82, v82
	v_exp_f32_e32 v83, v83
	v_exp_f32_e32 v84, v84
	v_exp_f32_e32 v85, v85
	v_exp_f32_e32 v86, v86
	v_exp_f32_e32 v87, v87
	v_add_f32_e32 v6, 0, v5
	v_add_f32_e32 v6, v7, v6
	v_add_f32_e32 v6, v9, v6
	v_add_f32_e32 v6, v11, v6
	v_add_f32_e32 v6, v12, v6
	v_add_f32_e32 v6, v13, v6
	v_add_f32_e32 v6, v14, v6
	v_add_f32_e32 v6, v15, v6
	v_add_f32_e32 v6, v16, v6
	v_add_f32_e32 v6, v17, v6
	v_add_f32_e32 v6, v82, v6
	v_add_f32_e32 v6, v83, v6
	v_add_f32_e32 v6, v84, v6
	v_add_f32_e32 v6, v85, v6
	v_add_f32_e32 v6, v86, v6
	v_add_f32_e32 v88, v87, v6
	v_fmac_f32_e32 v88, v133, v2
	v_cvt_pk_bf16_f32 v11, v9, v11
	v_cvt_pk_bf16_f32 v12, v12, v13
	v_cvt_pk_bf16_f32 v13, v14, v15
	v_cvt_pk_bf16_f32 v4, v16, v17
	v_cvt_pk_bf16_f32 v10, v5, v7
	v_cvt_pk_bf16_f32 v5, v82, v83
	v_cvt_pk_bf16_f32 v6, v84, v85
	v_cvt_pk_bf16_f32 v7, v86, v87
	v_mov_b32_e32 v133, v88
	v_mov_b32_e32 v138, v8
	s_waitcnt lgkmcnt(0)
	v_mfma_f32_32x32x16_bf16 v[66:81], v[210:213], v[10:13], v[66:81]
	v_mfma_f32_32x32x16_bf16 v[50:65], v[214:217], v[10:13], v[50:65]
	v_mfma_f32_32x32x16_bf16 v[34:49], v[218:221], v[10:13], v[34:49]
	v_mfma_f32_32x32x16_bf16 v[18:33], v[222:225], v[10:13], v[18:33]
	v_mfma_f32_32x32x16_bf16 v[66:81], v[226:229], v[4:7], v[66:81]
	v_mfma_f32_32x32x16_bf16 v[50:65], v[230:233], v[4:7], v[50:65]
	v_mfma_f32_32x32x16_bf16 v[34:49], v[234:237], v[4:7], v[34:49]
	v_mfma_f32_32x32x16_bf16 v[18:33], v[238:241], v[4:7], v[18:33]

.LBB0_407:
	s_andn2_b64 vcc, exec, s[0:1]
	v_mov_b32_e32 v4, 0xffff
	s_cbranch_vccnz .LBB0_409
	v_sub_u32_e32 v2, v132, v1
	v_mov_b32_e32 v5, 0x80
	v_subrev_u32_e32 v4, 0, v2
	v_subrev_u32_e32 v6, 1, v2
	v_subrev_u32_e32 v7, 2, v2
	v_subrev_u32_e32 v9, 3, v2
	v_cmp_ge_u32_e64 vcc, v5, v4
	v_cmp_ge_u32_e64 s[0:1], v5, v6
	v_cmp_ge_u32_e64 s[98:99], v5, v7
	v_cmp_ge_u32_e64 s[100:101], v5, v9
	v_cndmask_b32_e32 v82, v209, v82, vcc
	v_cndmask_b32_e64 v83, v209, v83, s[0:1]
	v_cndmask_b32_e64 v84, v209, v84, s[98:99]
	v_cndmask_b32_e64 v85, v209, v85, s[100:101]
	v_subrev_u32_e32 v4, 4, v2
	v_subrev_u32_e32 v6, 5, v2
	v_subrev_u32_e32 v7, 6, v2
	v_subrev_u32_e32 v9, 7, v2
	v_cmp_ge_u32_e64 vcc, v5, v4
	v_cmp_ge_u32_e64 s[0:1], v5, v6
	v_cmp_ge_u32_e64 s[98:99], v5, v7
	v_cmp_ge_u32_e64 s[100:101], v5, v9
	v_cndmask_b32_e32 v86, v209, v86, vcc
	v_cndmask_b32_e64 v87, v209, v87, s[0:1]
	v_cndmask_b32_e64 v88, v209, v88, s[98:99]
	v_cndmask_b32_e64 v89, v209, v89, s[100:101]
	v_subrev_u32_e32 v4, 16, v2
	v_subrev_u32_e32 v6, 17, v2
	v_subrev_u32_e32 v7, 18, v2
	v_subrev_u32_e32 v9, 19, v2
	v_cmp_ge_u32_e64 vcc, v5, v4
	v_cmp_ge_u32_e64 s[0:1], v5, v6
	v_cmp_ge_u32_e64 s[98:99], v5, v7
	v_cmp_ge_u32_e64 s[100:101], v5, v9
	v_cndmask_b32_e32 v90, v209, v90, vcc
	v_cndmask_b32_e64 v91, v209, v91, s[0:1]
	v_cndmask_b32_e64 v92, v209, v92, s[98:99]
	v_cndmask_b32_e64 v93, v209, v93, s[100:101]
	v_subrev_u32_e32 v4, 20, v2
	v_subrev_u32_e32 v6, 21, v2
	v_subrev_u32_e32 v7, 22, v2
	v_subrev_u32_e32 v9, 23, v2
	v_cmp_ge_u32_e64 vcc, v5, v4
	v_cmp_ge_u32_e64 s[0:1], v5, v6
	v_cmp_ge_u32_e64 s[98:99], v5, v7
	v_cmp_ge_u32_e64 s[100:101], v5, v9
	v_cndmask_b32_e32 v94, v209, v94, vcc
	v_cndmask_b32_e64 v95, v209, v95, s[0:1]
	v_cndmask_b32_e64 v96, v209, v96, s[98:99]
	v_cndmask_b32_e64 v97, v209, v97, s[100:101]
	v_max3_f32 v4, v82, s80, v83
	v_max3_f32 v4, v4, v84, v85
	v_max3_f32 v4, v4, v86, v87
	v_max3_f32 v4, v4, v88, v89
	v_max3_f32 v4, v4, v90, v91
	v_max3_f32 v4, v4, v92, v93
	v_max3_f32 v4, v4, v94, v95
	v_max3_f32 v2, v4, v96, v97
